# rw_prep record/gate/bonus stores marked nt (streaming outputs no longer evict cols tiles)
# speedup vs baseline: 1.2225x; 1.0128x over previous
; DEVINL float bflo(unsigned u) { return __uint_as_float(u << 16); }
; DEVINL float bfhi(unsigned u) { return __uint_as_float(u & 0xffff0000u); }
; DEVINL void rw_shift4(const char* colsb, float4 mu, unsigned o, int s, float (&out)[4]) {
;   const unsigned op = (s > 0) ? o - (unsigned)(NCP * 2) : o;
;   const unsigned on = (s < S_ - 1) ? o + (unsigned)(NCP * 2) : o;
;   const uint2 c = *(const uint2*)(colsb + o);
;   uint2 pv = *(const uint2*)(colsb + op);
;   uint2 nx = *(const uint2*)(colsb + on);
;   if (s == 0) pv = make_uint2(0u, 0u);
;   if (s == S_ - 1) nx = make_uint2(0u, 0u);
;   const float cu[4] = {bflo(c.x), bfhi(c.x), bflo(c.y), bfhi(c.y)};
;   const float pr[4] = {bflo(pv.x), bfhi(pv.x), bflo(pv.y), bfhi(pv.y)};
;   const float nn[4] = {bflo(nx.x), bfhi(nx.x), bflo(nx.y), bfhi(nx.y)};
;   const float m[4] = {mu.x, mu.y, mu.z, mu.w};
; #pragma unroll
;   for (int e = 0; e < 4; ++e) out[e] = cu[e] + m[e] * (0.5f * (pr[e] + nn[e]) - cu[e]);
; DEVINL void rw_prep_unit(const Params& p, int unit) {
;     ...
;       for (int j = 0; j < 4; ++j) {
;         int jo = j, zo = 0;
;         asm volatile("" : "+v"(jo), "+v"(zo));
;         const int t = tok0 + mt * 16 + 4 * g + jo;
;         const int s = t & (S_ - 1), b = t >> 12;
;         const unsigned c0 = (unsigned)(head * 64 + l15 * 4 + zo);
;         const unsigned rowo = (unsigned)t * (unsigned)(NCP * 2) + (unsigned)(C_RW * 2) + c0 * 2u;
;         float pr[4], pkr[4], pv[4];
;         rw_shift4(colsb, *(const float4*)(p.rw_mu + c0), rowo, s, pr);
;         rw_shift4(colsb, *(const float4*)(p.rw_mu + 1024u + c0), rowo + 2048u, s, pkr);
;         rw_shift4(colsb, *(const float4*)(p.rw_mu + 2048u + c0), rowo + 4096u, s, pv);
;         const float4 a0q = *(const float4*)(p.rw_a0 + c0), kkq = *(const float4*)(p.rw_k_k + c0);
;         const float4 kaq = *(const float4*)(p.rw_k_a + c0), rkq = *(const float4*)(p.rw_r_k + c0);
;         const float4 w0fq = *(const float4*)(p.rw_w0_f + c0), w0bq = *(const float4*)(p.rw_w0_b + c0);
;         const float a0v[4] = {a0q.x, a0q.y, a0q.z, a0q.w}, kkp[4] = {kkq.x, kkq.y, kkq.z, kkq.w};
;         const float kap[4] = {kaq.x, kaq.y, kaq.z, kaq.w}, rkp[4] = {rkq.x, rkq.y, rkq.z, rkq.w};
;         const float w0f[4] = {w0fq.x, w0fq.y, w0fq.z, w0fq.w}, w0b[4] = {w0bq.x, w0bq.y, w0bq.z, w0bq.w};
.LBB0_383:
	s_nop 0
	v_mov_b32_e32 v64, s40
	v_mov_b32_e32 v65, 0
	s_cmp_eq_u32 s40, 2
	v_add_u32_e32 v96, v65, v192
	v_add_u32_e32 v194, v193, v64
	v_lshlrev_b32_e32 v178, 1, v96
	v_and_b32_e32 v212, 0xfff, v194
	v_mad_u64_u32 v[72:73], s[0:1], v194, s49, v[178:179]
	v_add_u32_e32 v68, 0x1840, v72
	v_lshlrev_b64 v[74:75], 2, v[96:97]
	v_cmp_eq_u32_e32 vcc, 0, v212
	v_add_u32_e32 v69, 0xffffc440, v72
	v_lshl_add_u64 v[64:65], s[90:91], 0, v[74:75]
	v_cndmask_b32_e32 v70, v69, v68, vcc
	v_cmp_eq_u32_e64 s[0:1], s44, v212
	v_add_u32_e32 v69, 0x6c40, v72
	global_load_dwordx4 v[64:67], v[64:65], off
	v_cndmask_b32_e64 v73, v69, v68, s[0:1]
	global_load_dwordx2 v[68:69], v68, s[18:19]
	s_nop 0
	global_load_dwordx2 v[70:71], v70, s[18:19]
	s_nop 0
	global_load_dwordx2 v[76:77], v73, s[18:19]
	s_cselect_b64 s[6:7], -1, 0
	s_cmp_eq_u32 s40, 0
	s_cselect_b64 s[8:9], -1, 0
	v_cndmask_b32_e64 v223, v11, v10, s[6:7]
	v_cndmask_b32_e64 v223, v223, v8, s[8:9]
	s_waitcnt vmcnt(2)
	v_lshlrev_b32_e32 v209, 16, v68
	s_waitcnt vmcnt(1)
	v_cndmask_b32_e64 v70, v70, 0, vcc
	s_waitcnt vmcnt(0)
	v_cndmask_b32_e64 v73, v76, 0, s[0:1]
	v_cndmask_b32_e64 v76, v77, 0, s[0:1]
	v_and_b32_e32 v203, 0xffff0000, v68
	v_lshlrev_b32_e32 v68, 16, v70
	v_lshlrev_b32_e32 v77, 16, v73
	v_cndmask_b32_e64 v71, v71, 0, vcc
	v_lshlrev_b32_e32 v197, 16, v69
	v_and_b32_e32 v96, 0xffff0000, v69
	v_and_b32_e32 v69, 0xffff0000, v70
	v_and_b32_e32 v73, 0xffff0000, v73
	v_add_f32_e32 v68, v68, v77
	v_lshlrev_b32_e32 v70, 16, v71
	v_lshlrev_b32_e32 v78, 16, v76
	v_fma_f32 v210, v68, 0.5, -v209
	v_add_f32_e32 v68, v69, v73
	v_and_b32_e32 v71, 0xffff0000, v71
	v_and_b32_e32 v76, 0xffff0000, v76
	v_fma_f32 v204, v68, 0.5, -v203
	v_add_f32_e32 v68, v70, v78
	v_fma_f32 v198, v68, 0.5, -v197
	v_add_f32_e32 v68, v71, v76
	v_add_u32_e32 v73, 0x2040, v72
	v_add_u32_e32 v76, 0xffffcc40, v72
	v_cndmask_b32_e32 v78, v76, v73, vcc
	v_add_u32_e32 v76, 0x7440, v72
	v_fma_f32 v195, v68, 0.5, -v96
	v_lshl_add_u64 v[68:69], s[72:73], 0, v[74:75]
	v_cndmask_b32_e64 v80, v76, v73, s[0:1]
	global_load_dwordx4 v[68:71], v[68:69], off
	s_nop 0
	global_load_dwordx2 v[76:77], v73, s[18:19]
	s_nop 0
	global_load_dwordx2 v[78:79], v78, s[18:19]
	s_nop 0
	global_load_dwordx2 v[80:81], v80, s[18:19]
	v_fma_f32 v222, v64, v210, v209
	v_fma_f32 v221, v65, v204, v203
	v_fma_f32 v220, v66, v198, v197
	v_fma_f32 v219, v67, v195, v96
	s_waitcnt vmcnt(2)
	v_lshlrev_b32_e32 v215, 16, v76
	s_waitcnt vmcnt(1)
	v_cndmask_b32_e64 v73, v78, 0, vcc
	v_cndmask_b32_e64 v78, v79, 0, vcc
	s_waitcnt vmcnt(0)
	v_cndmask_b32_e64 v79, v80, 0, s[0:1]
	v_cndmask_b32_e64 v80, v81, 0, s[0:1]
	v_and_b32_e32 v208, 0xffff0000, v76
	v_lshlrev_b32_e32 v76, 16, v73
	v_lshlrev_b32_e32 v81, 16, v79
	v_add_f32_e32 v76, v76, v81
	v_and_b32_e32 v73, 0xffff0000, v73
	v_and_b32_e32 v79, 0xffff0000, v79
	v_fma_f32 v76, v76, 0.5, -v215
	v_fmac_f32_e32 v215, v68, v76
	v_add_f32_e32 v68, v73, v79
	v_lshlrev_b32_e32 v201, 16, v77
	v_and_b32_e32 v196, 0xffff0000, v77
	v_lshlrev_b32_e32 v77, 16, v78
	v_lshlrev_b32_e32 v82, 16, v80
	v_fma_f32 v68, v68, 0.5, -v208
	v_fmac_f32_e32 v208, v69, v68
	v_add_f32_e32 v68, v77, v82
	v_and_b32_e32 v78, 0xffff0000, v78
	v_and_b32_e32 v80, 0xffff0000, v80
	v_fma_f32 v68, v68, 0.5, -v201
	v_fmac_f32_e32 v201, v70, v68
	v_add_f32_e32 v68, v78, v80
	v_fma_f32 v68, v68, 0.5, -v196
	v_add_u32_e32 v73, 0x2840, v72
	v_add_u32_e32 v76, 0xffffd440, v72
	v_add_u32_e32 v72, 0x7c40, v72
	v_fmac_f32_e32 v196, v71, v68
	v_lshl_add_u64 v[68:69], s[78:79], 0, v[74:75]
	v_cndmask_b32_e32 v76, v76, v73, vcc
	v_cndmask_b32_e64 v78, v72, v73, s[0:1]
	global_load_dwordx4 v[68:71], v[68:69], off
	s_nop 0
	global_load_dwordx2 v[72:73], v73, s[18:19]
	s_nop 0
	global_load_dwordx2 v[76:77], v76, s[18:19]
	s_nop 0
	global_load_dwordx2 v[78:79], v78, s[18:19]
	s_waitcnt vmcnt(2)
	v_lshlrev_b32_e32 v216, 16, v72
	s_waitcnt vmcnt(1)
	v_cndmask_b32_e64 v76, v76, 0, vcc
	s_waitcnt vmcnt(0)
	v_cndmask_b32_e64 v78, v78, 0, s[0:1]
	v_and_b32_e32 v211, 0xffff0000, v72
	v_lshlrev_b32_e32 v72, 16, v76
	v_lshlrev_b32_e32 v80, 16, v78
	v_cndmask_b32_e64 v77, v77, 0, vcc
	v_cndmask_b32_e64 v79, v79, 0, s[0:1]
	v_lshlrev_b32_e32 v205, 16, v73
	v_and_b32_e32 v199, 0xffff0000, v73
	v_and_b32_e32 v73, 0xffff0000, v76
	v_and_b32_e32 v78, 0xffff0000, v78
	v_add_f32_e32 v72, v72, v80
	v_lshlrev_b32_e32 v76, 16, v77
	v_lshlrev_b32_e32 v81, 16, v79
	v_fma_f32 v218, v72, 0.5, -v216
	v_add_f32_e32 v72, v73, v78
	v_and_b32_e32 v77, 0xffff0000, v77
	v_and_b32_e32 v79, 0xffff0000, v79
	v_fma_f32 v214, v72, 0.5, -v211
	v_add_f32_e32 v72, v76, v81
	v_fma_f32 v207, v72, 0.5, -v205
	v_add_f32_e32 v72, v77, v79
	v_fma_f32 v202, v72, 0.5, -v199
	v_lshl_add_u64 v[72:73], s[20:21], 0, v[74:75]
	global_load_dwordx4 v[92:95], v[72:73], off
	v_lshl_add_u64 v[72:73], s[26:27], 0, v[74:75]
	global_load_dwordx4 v[88:91], v[72:73], off
	v_lshl_add_u64 v[72:73], s[60:61], 0, v[74:75]
	global_load_dwordx4 v[84:87], v[72:73], off
	v_lshl_add_u64 v[72:73], s[62:63], 0, v[74:75]
	global_load_dwordx4 v[80:83], v[72:73], off
	v_lshl_add_u64 v[72:73], s[12:13], 0, v[74:75]
	global_load_dwordx4 v[76:79], v[72:73], off
	v_lshl_add_u64 v[72:73], s[16:17], 0, v[74:75]
	global_load_dwordx4 v[72:75], v[72:73], off
	v_fma_f32 v217, v68, v218, v216
	v_fma_mixlo_f16 v68, v68, v218, v216
	v_fma_f32 v213, v69, v214, v211
	v_fma_mixlo_f16 v69, v69, v214, v211
	v_fma_f32 v206, v70, v207, v205
	v_fma_mixlo_f16 v70, v70, v207, v205
	v_fma_f32 v200, v71, v202, v199
	v_fma_mixlo_f16 v71, v71, v202, v199
	s_waitcnt vmcnt(5)
	v_add_f32_e32 v92, v92, v223
	v_mul_f32_e32 v92, 0xbfb8aa3b, v92
	v_exp_f32_e32 v92, v92
	s_waitcnt vmcnt(4)
; DEVINL float sigm(float x) { return 1.f / (1.f + __expf(-x)); }
; DEVINL void rw_prep_unit(const Params& p, int unit) {
;     ...
; #pragma unroll
;         for (int n = 0; n < 4; ++n) {
;           const float kraw = pkr[n];
;           float a = sigm(a0v[n] + sel4(aa[n], j));
;           av[n] = a;
;           float kk = kraw * kkp[n];
;           kkv[n] = kk;
;           n2 += kk * kk;
;           float k2 = kraw * (1.f + (a - 1.f) * kap[n]);
;           pk[n] = k2;
;           dot += pr[n] * k2 * rkp[n];
;         }
;         n2 = allred16(n2);
;         dot = allred16(dot);
;         const float inv = 1.f / fmaxf(sqrtf(n2), 1e-12f);
;         const unsigned reco = ((unsigned)((b * 16 + head) * 4096 + s)) * 1024u;
;         const unsigned tco = (unsigned)t * 2048u + c0 * 2u;
;         unsigned hwf[4], hwb[4], ha[4], hb[4], hk[4], hr[4], hv[4], bg[4], bbn[4];
; #pragma unroll
;         for (int n = 0; n < 4; ++n) {
;           float wf = __expf(-0.606531f * sigm(w0f[n] + sel4(awf[n], j)));
	v_mul_f32_e32 v89, v208, v89
	v_mul_f32_e32 v88, v215, v88
	v_mul_f32_e32 v90, v201, v90
	v_add_f32_e32 v92, 1.0, v92
	v_div_scale_f32 v223, s[0:1], v92, v92, 1.0
	v_rcp_f32_e32 v224, v223
	v_mul_f32_e32 v91, v196, v91
	v_fma_f32 v225, -v223, v224, 1.0
	v_fmac_f32_e32 v224, v225, v224
	v_div_scale_f32 v225, vcc, 1.0, v92, 1.0
	v_mul_f32_e32 v226, v225, v224
	v_fma_f32 v227, -v223, v226, v225
	v_fmac_f32_e32 v226, v227, v224
	v_fma_f32 v223, -v223, v226, v225
	v_div_fmas_f32 v223, v223, v224, v226
	v_div_fixup_f32 v92, v223, v92, 1.0
	v_add_f32_e32 v223, -1.0, v92
	s_waitcnt vmcnt(3)
	v_fma_f32 v84, v84, v223, 1.0
	v_mul_f32_e32 v223, v215, v84
	v_mul_f32_e32 v222, v222, v223
	s_waitcnt vmcnt(2)
	v_fma_f32 v80, v80, v222, 0
	v_cndmask_b32_e64 v222, v23, v22, s[6:7]
	v_cndmask_b32_e64 v222, v222, v20, s[8:9]
	v_add_f32_e32 v93, v93, v222
	v_mul_f32_e32 v93, 0xbfb8aa3b, v93
	v_exp_f32_e32 v93, v93
	v_fma_mixlo_f16 v84, v215, v84, 0
	v_add_f32_e32 v93, 1.0, v93
	v_div_scale_f32 v222, s[0:1], v93, v93, 1.0
	v_rcp_f32_e32 v223, v222
	s_nop 0
	v_fma_f32 v224, -v222, v223, 1.0
	v_fmac_f32_e32 v223, v224, v223
	v_div_scale_f32 v224, vcc, 1.0, v93, 1.0
	v_mul_f32_e32 v225, v224, v223
	v_fma_f32 v226, -v222, v225, v224
	v_fmac_f32_e32 v225, v226, v223
	v_fma_f32 v222, -v222, v225, v224
	v_div_fmas_f32 v222, v222, v223, v225
	v_div_fixup_f32 v93, v222, v93, 1.0
	v_add_f32_e32 v223, -1.0, v93
	v_fma_f32 v85, v85, v223, 1.0
	v_mul_f32_e32 v223, v208, v85
	v_mul_f32_e32 v221, v221, v223
	v_fmac_f32_e32 v80, v81, v221
	v_cndmask_b32_e64 v81, v35, v34, s[6:7]
	v_cndmask_b32_e64 v81, v81, v32, s[8:9]
	v_add_f32_e32 v81, v94, v81
	v_mul_f32_e32 v81, 0xbfb8aa3b, v81
	v_exp_f32_e32 v81, v81
	v_mul_f32_e32 v222, v89, v89
	v_fmac_f32_e32 v222, v88, v88
	v_fmac_f32_e32 v222, v90, v90
	v_add_f32_e32 v81, 1.0, v81
	v_div_scale_f32 v94, s[0:1], v81, v81, 1.0
	v_rcp_f32_e32 v221, v94
	v_fmac_f32_e32 v222, v91, v91
	v_fma_mixlo_f16 v85, v208, v85, 0
	v_fma_f32 v223, -v94, v221, 1.0
	v_fmac_f32_e32 v221, v223, v221
	v_div_scale_f32 v223, vcc, 1.0, v81, 1.0
	v_mul_f32_e32 v224, v223, v221
	v_fma_f32 v225, -v94, v224, v223
	v_fmac_f32_e32 v224, v225, v221
	v_fma_f32 v94, -v94, v224, v223
	v_div_fmas_f32 v94, v94, v221, v224
	v_div_fixup_f32 v81, v94, v81, 1.0
	v_add_f32_e32 v94, -1.0, v81
	v_fma_f32 v86, v86, v94, 1.0
	v_mul_f32_e32 v94, v201, v86
	v_mul_f32_e32 v94, v220, v94
	v_fmac_f32_e32 v80, v82, v94
	v_cndmask_b32_e64 v82, v47, v46, s[6:7]
	v_cndmask_b32_e64 v82, v82, v44, s[8:9]
	v_add_f32_e32 v82, v95, v82
	v_mul_f32_e32 v82, 0xbfb8aa3b, v82
	v_exp_f32_e32 v82, v82
	s_nop 0
	v_add_f32_e32 v82, 1.0, v82
	v_div_scale_f32 v94, s[0:1], v82, v82, 1.0
	v_rcp_f32_e32 v95, v94
	s_nop 0
	v_fma_f32 v220, -v94, v95, 1.0
	v_fmac_f32_e32 v95, v220, v95
	v_div_scale_f32 v220, vcc, 1.0, v82, 1.0
	v_mul_f32_e32 v221, v220, v95
	v_fma_f32 v223, -v94, v221, v220
	v_fmac_f32_e32 v221, v223, v95
	v_fma_f32 v94, -v94, v221, v220
	v_div_fmas_f32 v94, v94, v95, v221
	v_div_fixup_f32 v82, v94, v82, 1.0
	v_add_f32_e32 v94, -1.0, v82
	v_fma_f32 v87, v87, v94, 1.0
	v_mul_f32_e32 v94, v196, v87
	v_mul_f32_e32 v94, v219, v94
	v_fmac_f32_e32 v80, v83, v94
	v_add_f32_dpp v83, v222, v222 quad_perm:[1,0,3,2] row_mask:0xf bank_mask:0xf bound_ctrl:1
	s_nop 0
	v_add_f32_dpp v80, v80, v80 quad_perm:[1,0,3,2] row_mask:0xf bank_mask:0xf bound_ctrl:1
	v_add_f32_dpp v83, v83, v83 quad_perm:[2,3,0,1] row_mask:0xf bank_mask:0xf bound_ctrl:1
	s_nop 0
	v_add_f32_dpp v80, v80, v80 quad_perm:[2,3,0,1] row_mask:0xf bank_mask:0xf bound_ctrl:1
	v_add_f32_dpp v83, v83, v83 row_half_mirror row_mask:0xf bank_mask:0xf bound_ctrl:1
	s_nop 0
	v_add_f32_dpp v80, v80, v80 row_half_mirror row_mask:0xf bank_mask:0xf bound_ctrl:1
	v_add_f32_dpp v83, v83, v83 row_mirror row_mask:0xf bank_mask:0xf bound_ctrl:1
	v_cmp_gt_f32_e32 vcc, s50, v83
	v_mul_f32_e32 v94, 0x4f800000, v83
	v_add_f32_dpp v80, v80, v80 row_mirror row_mask:0xf bank_mask:0xf bound_ctrl:1
	v_cndmask_b32_e32 v83, v83, v94, vcc
	v_sqrt_f32_e32 v94, v83
	s_nop 0
	v_add_u32_e32 v95, -1, v94
	v_fma_f32 v219, -v95, v94, v83
	v_cmp_ge_f32_e64 s[0:1], 0, v219
	v_add_u32_e32 v219, 1, v94
	s_nop 0
	v_cndmask_b32_e64 v95, v94, v95, s[0:1]
	v_fma_f32 v94, -v219, v94, v83
	v_cmp_lt_f32_e64 s[0:1], 0, v94
	s_nop 1
	v_cndmask_b32_e64 v94, v95, v219, s[0:1]
	v_mul_f32_e32 v95, 0x37800000, v94
	v_cndmask_b32_e32 v94, v94, v95, vcc
	v_cmp_class_f32_e32 vcc, v83, v179
	s_nop 1
	v_cndmask_b32_e32 v83, v94, v83, vcc
	v_max_f32_e32 v83, 0x2b8cbccc, v83
	v_div_scale_f32 v94, s[0:1], v83, v83, 1.0
	v_rcp_f32_e32 v95, v94
	s_nop 0
	v_fma_f32 v219, -v94, v95, 1.0
	v_fmac_f32_e32 v95, v219, v95
	v_div_scale_f32 v219, vcc, 1.0, v83, 1.0
	v_mul_f32_e32 v220, v219, v95
	v_fma_f32 v221, -v94, v220, v219
	v_fmac_f32_e32 v220, v221, v95
	v_fma_f32 v94, -v94, v220, v219
	v_div_fmas_f32 v94, v94, v95, v220
	v_lshlrev_b32_e32 v95, 10, v212
	v_cndmask_b32_e64 v212, v3, v2, s[6:7]
	v_cndmask_b32_e64 v212, v212, v0, s[8:9]
	s_waitcnt vmcnt(1)
	v_add_f32_e32 v76, v76, v212
	v_mul_f32_e32 v76, 0xbfb8aa3b, v76
	v_exp_f32_e32 v76, v76
	v_div_fixup_f32 v83, v94, v83, 1.0
	v_mul_f32_e32 v88, v88, v83
	v_lshrrev_b32_e32 v94, 8, v194
	v_add_f32_e32 v76, 1.0, v76
	v_div_scale_f32 v212, s[0:1], v76, v76, 1.0
	v_rcp_f32_e32 v219, v212
	v_and_b32_e32 v94, 0x3f0, v94
	v_fma_f32 v220, -v212, v219, 1.0
	v_fmac_f32_e32 v219, v220, v219
	v_div_scale_f32 v220, vcc, 1.0, v76, 1.0
	v_mul_f32_e32 v221, v220, v219
	v_fma_f32 v222, -v212, v221, v220
	v_fmac_f32_e32 v221, v222, v219
	v_fma_f32 v212, -v212, v221, v220
	v_div_fmas_f32 v212, v212, v219, v221
	v_div_fixup_f32 v76, v212, v76, 1.0
	v_cndmask_b32_e64 v212, v7, v6, s[6:7]
	v_cndmask_b32_e64 v212, v212, v4, s[8:9]
	s_waitcnt vmcnt(0)
; DEVINL u16 f2bf(float a) { return (u16)(pk2(a, 0.f) & 0xffffu); }
; DEVINL float sigm(float x) { return 1.f / (1.f + __expf(-x)); }
; DEVINL void rw_prep_unit(const Params& p, int unit) {
;     ...
; #pragma unroll
;         for (int n = 0; n < 4; ++n) {
;           float wf = __expf(-0.606531f * sigm(w0f[n] + sel4(awf[n], j)));
;           float wb = __expf(-0.606531f * sigm(w0b[n] + sel4(awb[n], j)));
;           float kkn = kkv[n] * inv;
;           hwf[n] = f2h(wf); hwb[n] = f2h(wb); ha[n] = f2h(-kkn); hb[n] = f2h(kkn * av[n]);
;           hk[n] = f2h(pk[n]); hr[n] = f2h(pr[n]); hv[n] = f2h(pv[n]);
;           bg[n] = f2bf(sel4(ag[n], j)); bbn[n] = f2bf(dot * pv[n]);
;         }
	v_add_f32_e32 v72, v72, v212
	v_mul_f32_e32 v72, 0xbfb8aa3b, v72
	v_exp_f32_e32 v72, v72
	v_mul_f32_e32 v76, 0xbf1b459e, v76
	v_mul_f32_e32 v76, 0x3fb8aa3b, v76
	v_exp_f32_e32 v76, v76
	v_add_f32_e32 v72, 1.0, v72
	v_div_scale_f32 v212, s[0:1], v72, v72, 1.0
	v_rcp_f32_e32 v219, v212
	v_cvt_f16_f32_e32 v76, v76
	v_fma_f32 v220, -v212, v219, 1.0
	v_fmac_f32_e32 v219, v220, v219
	v_div_scale_f32 v220, vcc, 1.0, v72, 1.0
	v_mul_f32_e32 v221, v220, v219
	v_fma_f32 v222, -v212, v221, v220
	v_fmac_f32_e32 v221, v222, v219
	v_fma_f32 v212, -v212, v221, v220
	v_div_fmas_f32 v212, v212, v219, v221
	v_div_fixup_f32 v72, v212, v72, 1.0
	v_cvt_f16_f32_e64 v212, -v88
	v_fma_mixlo_f16 v88, v92, v88, 0
	v_fma_mixlo_f16 v92, v64, v210, v209
	v_cndmask_b32_e64 v64, v51, v50, s[6:7]
	v_cndmask_b32_e64 v64, v64, v48, s[8:9]
	v_cvt_pk_bf16_f32 v209, v64, s0
	v_mul_f32_e32 v64, v217, v80
	v_cvt_pk_bf16_f32 v210, v64, s0
	v_cndmask_b32_e64 v64, v15, v14, s[6:7]
	v_cndmask_b32_e64 v64, v64, v12, s[8:9]
	v_add_f32_e32 v64, v77, v64
	v_mul_f32_e32 v64, 0xbfb8aa3b, v64
	v_exp_f32_e32 v64, v64
	v_mul_f32_e32 v72, 0xbf1b459e, v72
	v_mul_f32_e32 v72, 0x3fb8aa3b, v72
	v_exp_f32_e32 v72, v72
	v_add_f32_e32 v64, 1.0, v64
	v_div_scale_f32 v77, s[0:1], v64, v64, 1.0
	v_rcp_f32_e32 v215, v77
	v_cvt_f16_f32_e32 v72, v72
	v_fma_f32 v216, -v77, v215, 1.0
	v_fmac_f32_e32 v215, v216, v215
	v_div_scale_f32 v216, vcc, 1.0, v64, 1.0
	v_mul_f32_e32 v217, v216, v215
	v_fma_f32 v218, -v77, v217, v216
	v_fmac_f32_e32 v217, v218, v215
	v_fma_f32 v77, -v77, v217, v216
	v_div_fmas_f32 v77, v77, v215, v217
	v_div_fixup_f32 v64, v77, v64, 1.0
	v_cndmask_b32_e64 v77, v19, v18, s[6:7]
	v_cndmask_b32_e64 v77, v77, v16, s[8:9]
	v_add_f32_e32 v73, v73, v77
	v_mul_f32_e32 v73, 0xbfb8aa3b, v73
	v_exp_f32_e32 v73, v73
	v_mul_f32_e32 v64, 0xbf1b459e, v64
	v_mul_f32_e32 v64, 0x3fb8aa3b, v64
	v_exp_f32_e32 v64, v64
	v_add_f32_e32 v73, 1.0, v73
	v_div_scale_f32 v77, s[0:1], v73, v73, 1.0
	v_rcp_f32_e32 v215, v77
	v_cvt_f16_f32_sdwa v64, v64 dst_sel:WORD_1 dst_unused:UNUSED_PAD src0_sel:DWORD
	v_fma_f32 v216, -v77, v215, 1.0
	v_fmac_f32_e32 v215, v216, v215
	v_div_scale_f32 v216, vcc, 1.0, v73, 1.0
	v_mul_f32_e32 v217, v216, v215
	v_fma_f32 v218, -v77, v217, v216
	v_fmac_f32_e32 v217, v218, v215
	v_fma_f32 v77, -v77, v217, v216
	v_div_fmas_f32 v77, v77, v215, v217
	v_div_fixup_f32 v73, v77, v73, 1.0
	v_mul_f32_e32 v77, v89, v83
	v_cvt_f16_f32_sdwa v89, -v77 dst_sel:WORD_1 dst_unused:UNUSED_PAD src0_sel:DWORD
	v_fma_mixlo_f16 v77, v93, v77, 0
	v_fma_mixlo_f16 v93, v65, v204, v203
	v_cndmask_b32_e64 v65, v55, v54, s[6:7]
	v_cndmask_b32_e64 v65, v65, v52, s[8:9]
	v_cvt_pk_bf16_f32 v203, v65, s0
	v_mul_f32_e32 v65, v213, v80
	v_cvt_pk_bf16_f32 v204, v65, s0
	v_cndmask_b32_e64 v65, v27, v26, s[6:7]
	v_cndmask_b32_e64 v65, v65, v24, s[8:9]
	v_add_f32_e32 v65, v78, v65
	v_mul_f32_e32 v65, 0xbfb8aa3b, v65
	v_exp_f32_e32 v65, v65
	v_mul_f32_e32 v73, 0xbf1b459e, v73
	v_mul_f32_e32 v73, 0x3fb8aa3b, v73
	v_exp_f32_e32 v73, v73
	v_add_f32_e32 v65, 1.0, v65
	v_div_scale_f32 v78, s[0:1], v65, v65, 1.0
	v_rcp_f32_e32 v208, v78
	v_cvt_f16_f32_sdwa v73, v73 dst_sel:WORD_1 dst_unused:UNUSED_PAD src0_sel:DWORD
	v_or_b32_e32 v64, v64, v76
	v_fma_f32 v211, -v78, v208, 1.0
	v_fmac_f32_e32 v208, v211, v208
	v_div_scale_f32 v211, vcc, 1.0, v65, 1.0
	v_mul_f32_e32 v213, v211, v208
	v_fma_f32 v214, -v78, v213, v211
	v_fmac_f32_e32 v213, v214, v208
	v_fma_f32 v78, -v78, v213, v211
	v_div_fmas_f32 v78, v78, v208, v213
	v_div_fixup_f32 v65, v78, v65, 1.0
	v_cndmask_b32_e64 v78, v31, v30, s[6:7]
	v_cndmask_b32_e64 v78, v78, v28, s[8:9]
	v_add_f32_e32 v74, v74, v78
	v_mul_f32_e32 v74, 0xbfb8aa3b, v74
	v_exp_f32_e32 v74, v74
	v_mul_f32_e32 v65, 0xbf1b459e, v65
	v_mul_f32_e32 v65, 0x3fb8aa3b, v65
	v_exp_f32_e32 v65, v65
	v_add_f32_e32 v74, 1.0, v74
	v_div_scale_f32 v78, s[0:1], v74, v74, 1.0
	v_rcp_f32_e32 v208, v78
	v_cvt_f16_f32_e32 v65, v65
	v_fma_f32 v211, -v78, v208, 1.0
	v_fmac_f32_e32 v208, v211, v208
	v_div_scale_f32 v211, vcc, 1.0, v74, 1.0
	v_mul_f32_e32 v213, v211, v208
	v_fma_f32 v214, -v78, v213, v211
	v_fmac_f32_e32 v213, v214, v208
	v_fma_f32 v78, -v78, v213, v211
	v_div_fmas_f32 v78, v78, v208, v213
	v_div_fixup_f32 v74, v78, v74, 1.0
	v_mul_f32_e32 v78, v90, v83
	v_cvt_f16_f32_e64 v90, -v78
	v_fma_mixlo_f16 v78, v81, v78, 0
	v_fma_mixlo_f16 v81, v201, v86, 0
	v_fma_mixlo_f16 v86, v66, v198, v197
	v_cndmask_b32_e64 v66, v59, v58, s[6:7]
	v_cndmask_b32_e64 v66, v66, v56, s[8:9]
	v_cvt_pk_bf16_f32 v197, v66, s0
	v_mul_f32_e32 v66, v206, v80
	v_cvt_pk_bf16_f32 v198, v66, s0
	v_cndmask_b32_e64 v66, v39, v38, s[6:7]
	v_cndmask_b32_e64 v66, v66, v36, s[8:9]
	v_add_f32_e32 v66, v79, v66
	v_mul_f32_e32 v66, 0xbfb8aa3b, v66
	v_exp_f32_e32 v66, v66
	v_mul_f32_e32 v74, 0xbf1b459e, v74
	v_mul_f32_e32 v74, 0x3fb8aa3b, v74
	v_exp_f32_e32 v74, v74
	v_add_f32_e32 v66, 1.0, v66
	v_div_scale_f32 v79, s[0:1], v66, v66, 1.0
	v_rcp_f32_e32 v201, v79
	v_cvt_f16_f32_e32 v74, v74
	v_fma_f32 v205, -v79, v201, 1.0
	v_fmac_f32_e32 v201, v205, v201
	v_div_scale_f32 v205, vcc, 1.0, v66, 1.0
	v_mul_f32_e32 v206, v205, v201
	v_fma_f32 v207, -v79, v206, v205
	v_fmac_f32_e32 v206, v207, v201
	v_fma_f32 v79, -v79, v206, v205
	v_div_fmas_f32 v79, v79, v201, v206
	v_div_fixup_f32 v66, v79, v66, 1.0
	v_cndmask_b32_e64 v79, v43, v42, s[6:7]
	v_cndmask_b32_e64 v79, v79, v40, s[8:9]
	v_add_f32_e32 v75, v75, v79
	v_mul_f32_e32 v75, 0xbfb8aa3b, v75
	v_exp_f32_e32 v75, v75
	v_mul_f32_e32 v66, 0xbf1b459e, v66
	v_mul_f32_e32 v66, 0x3fb8aa3b, v66
	v_exp_f32_e32 v66, v66
	v_add_f32_e32 v75, 1.0, v75
	v_div_scale_f32 v79, s[0:1], v75, v75, 1.0
	v_rcp_f32_e32 v201, v79
; DEVINL void rw_prep_unit(const Params& p, int unit) {
;     ...
;       for (int j = 0; j < 4; ++j) {
;         int jo = j, zo = 0;
;         asm volatile("" : "+v"(jo), "+v"(zo));
;         const int t = tok0 + mt * 16 + 4 * g + jo;
;         const int s = t & (S_ - 1), b = t >> 12;
;         const unsigned c0 = (unsigned)(head * 64 + l15 * 4 + zo);
;         const unsigned rowo = (unsigned)t * (unsigned)(NCP * 2) + (unsigned)(C_RW * 2) + c0 * 2u;
;         float pr[4], pkr[4], pv[4];
;         rw_shift4(colsb, *(const float4*)(p.rw_mu + c0), rowo, s, pr);
;         rw_shift4(colsb, *(const float4*)(p.rw_mu + 1024u + c0), rowo + 2048u, s, pkr);
;         rw_shift4(colsb, *(const float4*)(p.rw_mu + 2048u + c0), rowo + 4096u, s, pv);
;     ...
;         char* rb = ws + O_REC + (reco + (unsigned)l15 * 64u);
;         *(uint4*)(rb) = make_uint4(hwf[0] | (hwf[1] << 16), hwf[2] | (hwf[3] << 16), hwb[0] | (hwb[1] << 16), hwb[2] | (hwb[3] << 16));
;         *(uint4*)(rb + 16) = make_uint4(ha[0] | (ha[1] << 16), ha[2] | (ha[3] << 16), hb[0] | (hb[1] << 16), hb[2] | (hb[3] << 16));
;         *(uint4*)(rb + 32) = make_uint4(hk[0] | (hk[1] << 16), hk[2] | (hk[3] << 16), hr[0] | (hr[1] << 16), hr[2] | (hr[3] << 16));
;         *(uint2*)(rb + 48) = make_uint2(hv[0] | (hv[1] << 16), hv[2] | (hv[3] << 16));
;         *(uint2*)(ws + O_GRW + tco) = make_uint2(bg[0] | (bg[1] << 16), bg[2] | (bg[3] << 16));
;         *(uint2*)(ws + O_BONUS + tco) = make_uint2(bbn[0] | (bbn[1] << 16), bbn[2] | (bbn[3] << 16));
	v_cvt_f16_f32_sdwa v66, v66 dst_sel:WORD_1 dst_unused:UNUSED_PAD src0_sel:DWORD
	v_fma_f32 v205, -v79, v201, 1.0
	v_fmac_f32_e32 v201, v205, v201
	v_div_scale_f32 v205, vcc, 1.0, v75, 1.0
	v_mul_f32_e32 v206, v205, v201
	v_fma_f32 v207, -v79, v206, v205
	v_fmac_f32_e32 v206, v207, v201
	v_fma_f32 v79, -v79, v206, v205
	v_div_fmas_f32 v79, v79, v201, v206
	v_div_fixup_f32 v75, v79, v75, 1.0
	v_mul_f32_e32 v75, 0xbf1b459e, v75
	v_mul_f32_e32 v75, 0x3fb8aa3b, v75
	v_exp_f32_e32 v75, v75
	v_mul_f32_e32 v79, v91, v83
	v_cvt_f16_f32_sdwa v83, -v79 dst_sel:WORD_1 dst_unused:UNUSED_PAD src0_sel:DWORD
	v_fma_mixlo_f16 v79, v82, v79, 0
	v_cvt_f16_f32_sdwa v75, v75 dst_sel:WORD_1 dst_unused:UNUSED_PAD src0_sel:DWORD
	v_fma_mixlo_f16 v82, v196, v87, 0
	v_fma_mixlo_f16 v87, v67, v195, v96
	v_cndmask_b32_e64 v67, v63, v62, s[6:7]
	v_cndmask_b32_e64 v67, v67, v60, s[8:9]
	v_cvt_pk_bf16_f32 v91, v67, s0
	v_mul_f32_e32 v67, v200, v80
	v_cvt_pk_bf16_f32 v80, v67, s0
	v_add_lshl_u32 v67, v94, v191, 22
	v_or3_b32 v95, v67, v95, v186
	v_or_b32_e32 v65, v66, v65
	v_or_b32_e32 v67, v75, v74
	v_or_b32_e32 v66, v73, v72
	global_store_dwordx4 v95, v[64:67], s[36:37] nt
	v_lshlrev_b32_e32 v72, 16, v77
	v_lshl_add_u32 v94, v194, 11, v178
	v_lshlrev_b32_e32 v66, 16, v79
	v_or_b32_e32 v65, v83, v90
	v_or_b32_e32 v64, v89, v212
	v_or_b32_sdwa v67, v66, v78 dst_sel:DWORD dst_unused:UNUSED_PAD src0_sel:DWORD src1_sel:WORD_0
	v_or_b32_sdwa v66, v72, v88 dst_sel:DWORD dst_unused:UNUSED_PAD src0_sel:DWORD src1_sel:WORD_0
	global_store_dwordx4 v95, v[64:67], s[36:37] offset:256 nt
	v_lshlrev_b32_e32 v72, 16, v93
	s_add_i32 s6, s40, 1
	v_lshlrev_b32_e32 v64, 16, v82
	v_lshlrev_b32_e32 v66, 16, v85
	v_lshlrev_b32_e32 v67, 16, v87
	v_or_b32_sdwa v65, v64, v81 dst_sel:DWORD dst_unused:UNUSED_PAD src0_sel:DWORD src1_sel:WORD_0
	v_or_b32_sdwa v64, v66, v84 dst_sel:DWORD dst_unused:UNUSED_PAD src0_sel:DWORD src1_sel:WORD_0
	v_or_b32_sdwa v67, v67, v86 dst_sel:DWORD dst_unused:UNUSED_PAD src0_sel:DWORD src1_sel:WORD_0
	v_or_b32_sdwa v66, v72, v92 dst_sel:DWORD dst_unused:UNUSED_PAD src0_sel:DWORD src1_sel:WORD_0
	global_store_dwordx4 v95, v[64:67], s[36:37] offset:512 nt
	s_cmp_eq_u32 s6, 1
	s_nop 0
	v_lshlrev_b32_e32 v64, 16, v71
	v_lshlrev_b32_e32 v66, 16, v69
	v_or_b32_sdwa v65, v64, v70 dst_sel:DWORD dst_unused:UNUSED_PAD src0_sel:DWORD src1_sel:WORD_0
	v_or_b32_sdwa v64, v66, v68 dst_sel:DWORD dst_unused:UNUSED_PAD src0_sel:DWORD src1_sel:WORD_0
	global_store_dwordx2 v95, v[64:65], s[36:37] offset:768 nt
	v_lshlrev_b32_e32 v64, 16, v91
	v_lshlrev_b32_e32 v66, 16, v203
	v_or_b32_sdwa v65, v64, v197 dst_sel:DWORD dst_unused:UNUSED_PAD src0_sel:DWORD src1_sel:WORD_0
	v_or_b32_sdwa v64, v66, v209 dst_sel:DWORD dst_unused:UNUSED_PAD src0_sel:DWORD src1_sel:WORD_0
	global_store_dwordx2 v94, v[64:65], s[38:39] nt
	v_lshlrev_b32_e32 v64, 16, v80
	v_lshlrev_b32_e32 v66, 16, v204
	v_or_b32_sdwa v65, v64, v198 dst_sel:DWORD dst_unused:UNUSED_PAD src0_sel:DWORD src1_sel:WORD_0
	v_or_b32_sdwa v64, v66, v210 dst_sel:DWORD dst_unused:UNUSED_PAD src0_sel:DWORD src1_sel:WORD_0
	global_store_dwordx2 v94, v[64:65], s[70:71] nt
	v_mov_b32_e32 v64, s6
	v_mov_b32_e32 v65, v97
	s_cselect_b64 s[6:7], -1, 0
	v_add_u32_e32 v96, v65, v192
	v_add_u32_e32 v194, v193, v64
	v_lshlrev_b32_e32 v178, 1, v96
	v_and_b32_e32 v212, 0xfff, v194
	v_mad_u64_u32 v[72:73], s[0:1], v194, s49, v[178:179]
	v_add_u32_e32 v68, 0x1840, v72
	v_lshlrev_b64 v[74:75], 2, v[96:97]
	v_cmp_eq_u32_e32 vcc, 0, v212
	v_add_u32_e32 v69, 0xffffc440, v72
	v_lshl_add_u64 v[64:65], s[90:91], 0, v[74:75]
	v_cndmask_b32_e32 v70, v69, v68, vcc
	v_cmp_eq_u32_e64 s[0:1], s44, v212
	v_add_u32_e32 v69, 0x6c40, v72
	global_load_dwordx4 v[64:67], v[64:65], off
	v_cndmask_b32_e64 v73, v69, v68, s[0:1]
	global_load_dwordx2 v[68:69], v68, s[18:19]
	s_nop 0
	global_load_dwordx2 v[70:71], v70, s[18:19]
	s_nop 0
	global_load_dwordx2 v[76:77], v73, s[18:19]
	v_cndmask_b32_e64 v223, v11, v9, s[6:7]
	s_add_i32 s40, s40, 2
	s_cmp_eq_u32 s40, 4
	s_waitcnt vmcnt(2)
	v_lshlrev_b32_e32 v209, 16, v68
	s_waitcnt vmcnt(1)
	v_cndmask_b32_e64 v70, v70, 0, vcc
	s_waitcnt vmcnt(0)
	v_cndmask_b32_e64 v73, v76, 0, s[0:1]
	v_cndmask_b32_e64 v76, v77, 0, s[0:1]
	v_and_b32_e32 v203, 0xffff0000, v68
	v_lshlrev_b32_e32 v68, 16, v70
	v_lshlrev_b32_e32 v77, 16, v73
	v_cndmask_b32_e64 v71, v71, 0, vcc
	v_lshlrev_b32_e32 v197, 16, v69
	v_and_b32_e32 v96, 0xffff0000, v69
	v_and_b32_e32 v69, 0xffff0000, v70
	v_and_b32_e32 v73, 0xffff0000, v73
	v_add_f32_e32 v68, v68, v77
	v_lshlrev_b32_e32 v70, 16, v71
	v_lshlrev_b32_e32 v78, 16, v76
	v_fma_f32 v210, v68, 0.5, -v209
	v_add_f32_e32 v68, v69, v73
	v_and_b32_e32 v71, 0xffff0000, v71
	v_and_b32_e32 v76, 0xffff0000, v76
	v_fma_f32 v204, v68, 0.5, -v203
	v_add_f32_e32 v68, v70, v78
	v_fma_f32 v198, v68, 0.5, -v197
	v_add_f32_e32 v68, v71, v76
	v_add_u32_e32 v73, 0x2040, v72
	v_add_u32_e32 v76, 0xffffcc40, v72
	v_cndmask_b32_e32 v78, v76, v73, vcc
	v_add_u32_e32 v76, 0x7440, v72
	v_fma_f32 v195, v68, 0.5, -v96
	v_lshl_add_u64 v[68:69], s[72:73], 0, v[74:75]
	v_cndmask_b32_e64 v80, v76, v73, s[0:1]
	global_load_dwordx4 v[68:71], v[68:69], off
	s_nop 0
	global_load_dwordx2 v[76:77], v73, s[18:19]
	s_nop 0
	global_load_dwordx2 v[78:79], v78, s[18:19]
	s_nop 0
	global_load_dwordx2 v[80:81], v80, s[18:19]
	v_fma_f32 v222, v64, v210, v209
	v_fma_f32 v221, v65, v204, v203
	v_fma_f32 v220, v66, v198, v197
	v_fma_f32 v219, v67, v195, v96
	s_waitcnt vmcnt(2)
	v_lshlrev_b32_e32 v214, 16, v76
	s_waitcnt vmcnt(1)
	v_cndmask_b32_e64 v73, v78, 0, vcc
	v_cndmask_b32_e64 v78, v79, 0, vcc
	s_waitcnt vmcnt(0)
; DEVINL float sigm(float x) { return 1.f / (1.f + __expf(-x)); }
; DEVINL void rw_prep_unit(const Params& p, int unit) {
;     ...
;         rw_shift4(colsb, *(const float4*)(p.rw_mu + c0), rowo, s, pr);
;         rw_shift4(colsb, *(const float4*)(p.rw_mu + 1024u + c0), rowo + 2048u, s, pkr);
;         rw_shift4(colsb, *(const float4*)(p.rw_mu + 2048u + c0), rowo + 4096u, s, pv);
;         const float4 a0q = *(const float4*)(p.rw_a0 + c0), kkq = *(const float4*)(p.rw_k_k + c0);
;         const float4 kaq = *(const float4*)(p.rw_k_a + c0), rkq = *(const float4*)(p.rw_r_k + c0);
;         const float4 w0fq = *(const float4*)(p.rw_w0_f + c0), w0bq = *(const float4*)(p.rw_w0_b + c0);
;         const float a0v[4] = {a0q.x, a0q.y, a0q.z, a0q.w}, kkp[4] = {kkq.x, kkq.y, kkq.z, kkq.w};
;         const float kap[4] = {kaq.x, kaq.y, kaq.z, kaq.w}, rkp[4] = {rkq.x, rkq.y, rkq.z, rkq.w};
;         const float w0f[4] = {w0fq.x, w0fq.y, w0fq.z, w0fq.w}, w0b[4] = {w0bq.x, w0bq.y, w0bq.z, w0bq.w};
;         float pk[4], av[4], kkv[4];
;         float n2 = 0.f, dot = 0.f;
; #pragma unroll
;         for (int n = 0; n < 4; ++n) {
;           const float kraw = pkr[n];
;           float a = sigm(a0v[n] + sel4(aa[n], j));
;           av[n] = a;
;           float kk = kraw * kkp[n];
;           kkv[n] = kk;
;           n2 += kk * kk;
;           float k2 = kraw * (1.f + (a - 1.f) * kap[n]);
;           pk[n] = k2;
;           dot += pr[n] * k2 * rkp[n];
;         }
;         n2 = allred16(n2);
;         dot = allred16(dot);
	v_cndmask_b32_e64 v79, v80, 0, s[0:1]
	v_cndmask_b32_e64 v80, v81, 0, s[0:1]
	v_and_b32_e32 v206, 0xffff0000, v76
	v_lshlrev_b32_e32 v76, 16, v73
	v_lshlrev_b32_e32 v81, 16, v79
	v_add_f32_e32 v76, v76, v81
	v_and_b32_e32 v73, 0xffff0000, v73
	v_and_b32_e32 v79, 0xffff0000, v79
	v_fma_f32 v76, v76, 0.5, -v214
	v_fmac_f32_e32 v214, v68, v76
	v_add_f32_e32 v68, v73, v79
	v_lshlrev_b32_e32 v200, 16, v77
	v_and_b32_e32 v196, 0xffff0000, v77
	v_lshlrev_b32_e32 v77, 16, v78
	v_lshlrev_b32_e32 v82, 16, v80
	v_fma_f32 v68, v68, 0.5, -v206
	v_fmac_f32_e32 v206, v69, v68
	v_add_f32_e32 v68, v77, v82
	v_and_b32_e32 v78, 0xffff0000, v78
	v_and_b32_e32 v80, 0xffff0000, v80
	v_fma_f32 v68, v68, 0.5, -v200
	v_fmac_f32_e32 v200, v70, v68
	v_add_f32_e32 v68, v78, v80
	v_fma_f32 v68, v68, 0.5, -v196
	v_add_u32_e32 v73, 0x2840, v72
	v_add_u32_e32 v76, 0xffffd440, v72
	v_add_u32_e32 v72, 0x7c40, v72
	v_fmac_f32_e32 v196, v71, v68
	v_lshl_add_u64 v[68:69], s[78:79], 0, v[74:75]
	v_cndmask_b32_e32 v76, v76, v73, vcc
	v_cndmask_b32_e64 v78, v72, v73, s[0:1]
	global_load_dwordx4 v[68:71], v[68:69], off
	s_nop 0
	global_load_dwordx2 v[72:73], v73, s[18:19]
	s_nop 0
	global_load_dwordx2 v[76:77], v76, s[18:19]
	s_nop 0
	global_load_dwordx2 v[78:79], v78, s[18:19]
	s_waitcnt vmcnt(2)
	v_lshlrev_b32_e32 v216, 16, v72
	s_waitcnt vmcnt(1)
	v_cndmask_b32_e64 v76, v76, 0, vcc
	s_waitcnt vmcnt(0)
	v_cndmask_b32_e64 v78, v78, 0, s[0:1]
	v_and_b32_e32 v211, 0xffff0000, v72
	v_lshlrev_b32_e32 v72, 16, v76
	v_lshlrev_b32_e32 v80, 16, v78
	v_cndmask_b32_e64 v77, v77, 0, vcc
	v_cndmask_b32_e64 v79, v79, 0, s[0:1]
	v_lshlrev_b32_e32 v205, 16, v73
	v_and_b32_e32 v199, 0xffff0000, v73
	v_and_b32_e32 v73, 0xffff0000, v76
	v_and_b32_e32 v78, 0xffff0000, v78
	v_add_f32_e32 v72, v72, v80
	v_lshlrev_b32_e32 v76, 16, v77
	v_lshlrev_b32_e32 v81, 16, v79
	v_fma_f32 v218, v72, 0.5, -v216
	v_add_f32_e32 v72, v73, v78
	v_and_b32_e32 v77, 0xffff0000, v77
	v_and_b32_e32 v79, 0xffff0000, v79
	v_fma_f32 v215, v72, 0.5, -v211
	v_add_f32_e32 v72, v76, v81
	v_fma_f32 v208, v72, 0.5, -v205
	v_add_f32_e32 v72, v77, v79
	v_fma_f32 v202, v72, 0.5, -v199
	v_lshl_add_u64 v[72:73], s[20:21], 0, v[74:75]
	global_load_dwordx4 v[92:95], v[72:73], off
	v_lshl_add_u64 v[72:73], s[26:27], 0, v[74:75]
	global_load_dwordx4 v[88:91], v[72:73], off
	v_lshl_add_u64 v[72:73], s[60:61], 0, v[74:75]
	global_load_dwordx4 v[84:87], v[72:73], off
	v_lshl_add_u64 v[72:73], s[62:63], 0, v[74:75]
	global_load_dwordx4 v[80:83], v[72:73], off
	v_lshl_add_u64 v[72:73], s[12:13], 0, v[74:75]
	global_load_dwordx4 v[76:79], v[72:73], off
	v_lshl_add_u64 v[72:73], s[16:17], 0, v[74:75]
	global_load_dwordx4 v[72:75], v[72:73], off
	v_fma_f32 v217, v68, v218, v216
	v_fma_mixlo_f16 v68, v68, v218, v216
	v_fma_f32 v213, v69, v215, v211
	v_fma_mixlo_f16 v69, v69, v215, v211
	v_fma_f32 v207, v70, v208, v205
	v_fma_mixlo_f16 v70, v70, v208, v205
	v_fma_f32 v201, v71, v202, v199
	v_fma_mixlo_f16 v71, v71, v202, v199
	s_waitcnt vmcnt(5)
	v_add_f32_e32 v92, v92, v223
	v_mul_f32_e32 v92, 0xbfb8aa3b, v92
	v_exp_f32_e32 v92, v92
	s_waitcnt vmcnt(4)
	v_mul_f32_e32 v89, v206, v89
	v_mul_f32_e32 v88, v214, v88
	v_mul_f32_e32 v90, v200, v90
	v_add_f32_e32 v92, 1.0, v92
	v_div_scale_f32 v223, s[0:1], v92, v92, 1.0
	v_rcp_f32_e32 v224, v223
	v_mul_f32_e32 v91, v196, v91
	v_fma_f32 v225, -v223, v224, 1.0
	v_fmac_f32_e32 v224, v225, v224
	v_div_scale_f32 v225, vcc, 1.0, v92, 1.0
	v_mul_f32_e32 v226, v225, v224
	v_fma_f32 v227, -v223, v226, v225
	v_fmac_f32_e32 v226, v227, v224
	v_fma_f32 v223, -v223, v226, v225
	v_div_fmas_f32 v223, v223, v224, v226
	v_div_fixup_f32 v92, v223, v92, 1.0
	v_add_f32_e32 v223, -1.0, v92
	s_waitcnt vmcnt(3)
	v_fma_f32 v84, v84, v223, 1.0
	v_mul_f32_e32 v223, v214, v84
	v_mul_f32_e32 v222, v222, v223
	s_waitcnt vmcnt(2)
	v_fma_f32 v80, v80, v222, 0
	v_cndmask_b32_e64 v222, v23, v21, s[6:7]
	v_add_f32_e32 v93, v93, v222
	v_mul_f32_e32 v93, 0xbfb8aa3b, v93
	v_exp_f32_e32 v93, v93
	v_fma_mixlo_f16 v84, v214, v84, 0
	v_add_f32_e32 v93, 1.0, v93
	v_div_scale_f32 v222, s[0:1], v93, v93, 1.0
	v_rcp_f32_e32 v223, v222
	s_nop 0
	v_fma_f32 v224, -v222, v223, 1.0
	v_fmac_f32_e32 v223, v224, v223
	v_div_scale_f32 v224, vcc, 1.0, v93, 1.0
	v_mul_f32_e32 v225, v224, v223
	v_fma_f32 v226, -v222, v225, v224
	v_fmac_f32_e32 v225, v226, v223
	v_fma_f32 v222, -v222, v225, v224
	v_div_fmas_f32 v222, v222, v223, v225
	v_div_fixup_f32 v93, v222, v93, 1.0
	v_add_f32_e32 v223, -1.0, v93
	v_fma_f32 v85, v85, v223, 1.0
	v_mul_f32_e32 v223, v206, v85
	v_mul_f32_e32 v221, v221, v223
	v_fmac_f32_e32 v80, v81, v221
	v_cndmask_b32_e64 v81, v35, v33, s[6:7]
	v_add_f32_e32 v81, v94, v81
	v_mul_f32_e32 v81, 0xbfb8aa3b, v81
	v_exp_f32_e32 v81, v81
	v_mul_f32_e32 v222, v89, v89
	v_fmac_f32_e32 v222, v88, v88
	v_fmac_f32_e32 v222, v90, v90
	v_add_f32_e32 v81, 1.0, v81
	v_div_scale_f32 v94, s[0:1], v81, v81, 1.0
	v_rcp_f32_e32 v221, v94
	v_fmac_f32_e32 v222, v91, v91
	v_fma_mixlo_f16 v85, v206, v85, 0
	v_fma_f32 v223, -v94, v221, 1.0
	v_fmac_f32_e32 v221, v223, v221
	v_div_scale_f32 v223, vcc, 1.0, v81, 1.0
	v_mul_f32_e32 v224, v223, v221
	v_fma_f32 v225, -v94, v224, v223
	v_fmac_f32_e32 v224, v225, v221
	v_fma_f32 v94, -v94, v224, v223
	v_div_fmas_f32 v94, v94, v221, v224
	v_div_fixup_f32 v81, v94, v81, 1.0
	v_add_f32_e32 v94, -1.0, v81
	v_fma_f32 v86, v86, v94, 1.0
	v_mul_f32_e32 v94, v200, v86
	v_mul_f32_e32 v94, v220, v94
	v_fmac_f32_e32 v80, v82, v94
	v_cndmask_b32_e64 v82, v47, v45, s[6:7]
	v_add_f32_e32 v82, v95, v82
	v_mul_f32_e32 v82, 0xbfb8aa3b, v82
	v_exp_f32_e32 v82, v82
	s_nop 0
	v_add_f32_e32 v82, 1.0, v82
	v_div_scale_f32 v94, s[0:1], v82, v82, 1.0
; DEVINL float sigm(float x) { return 1.f / (1.f + __expf(-x)); }
; DEVINL void rw_prep_unit(const Params& p, int unit) {
;     ...
;         n2 = allred16(n2);
;         dot = allred16(dot);
;         const float inv = 1.f / fmaxf(sqrtf(n2), 1e-12f);
;         const unsigned reco = ((unsigned)((b * 16 + head) * 4096 + s)) * 1024u;
;         const unsigned tco = (unsigned)t * 2048u + c0 * 2u;
;         unsigned hwf[4], hwb[4], ha[4], hb[4], hk[4], hr[4], hv[4], bg[4], bbn[4];
; #pragma unroll
;         for (int n = 0; n < 4; ++n) {
;           float wf = __expf(-0.606531f * sigm(w0f[n] + sel4(awf[n], j)));
;           float wb = __expf(-0.606531f * sigm(w0b[n] + sel4(awb[n], j)));
;           float kkn = kkv[n] * inv;
;           hwf[n] = f2h(wf); hwb[n] = f2h(wb); ha[n] = f2h(-kkn); hb[n] = f2h(kkn * av[n]);
	v_rcp_f32_e32 v95, v94
	s_nop 0
	v_fma_f32 v220, -v94, v95, 1.0
	v_fmac_f32_e32 v95, v220, v95
	v_div_scale_f32 v220, vcc, 1.0, v82, 1.0
	v_mul_f32_e32 v221, v220, v95
	v_fma_f32 v223, -v94, v221, v220
	v_fmac_f32_e32 v221, v223, v95
	v_fma_f32 v94, -v94, v221, v220
	v_div_fmas_f32 v94, v94, v95, v221
	v_div_fixup_f32 v82, v94, v82, 1.0
	v_add_f32_e32 v94, -1.0, v82
	v_fma_f32 v87, v87, v94, 1.0
	v_mul_f32_e32 v94, v196, v87
	v_mul_f32_e32 v94, v219, v94
	v_fmac_f32_e32 v80, v83, v94
	v_add_f32_dpp v83, v222, v222 quad_perm:[1,0,3,2] row_mask:0xf bank_mask:0xf bound_ctrl:1
	s_nop 0
	v_add_f32_dpp v80, v80, v80 quad_perm:[1,0,3,2] row_mask:0xf bank_mask:0xf bound_ctrl:1
	v_add_f32_dpp v83, v83, v83 quad_perm:[2,3,0,1] row_mask:0xf bank_mask:0xf bound_ctrl:1
	s_nop 0
	v_add_f32_dpp v80, v80, v80 quad_perm:[2,3,0,1] row_mask:0xf bank_mask:0xf bound_ctrl:1
	v_add_f32_dpp v83, v83, v83 row_half_mirror row_mask:0xf bank_mask:0xf bound_ctrl:1
	s_nop 0
	v_add_f32_dpp v80, v80, v80 row_half_mirror row_mask:0xf bank_mask:0xf bound_ctrl:1
	v_add_f32_dpp v83, v83, v83 row_mirror row_mask:0xf bank_mask:0xf bound_ctrl:1
	v_cmp_gt_f32_e32 vcc, s50, v83
	v_mul_f32_e32 v94, 0x4f800000, v83
	v_add_f32_dpp v80, v80, v80 row_mirror row_mask:0xf bank_mask:0xf bound_ctrl:1
	v_cndmask_b32_e32 v83, v83, v94, vcc
	v_sqrt_f32_e32 v94, v83
	s_nop 0
	v_add_u32_e32 v95, -1, v94
	v_fma_f32 v219, -v95, v94, v83
	v_cmp_ge_f32_e64 s[0:1], 0, v219
	v_add_u32_e32 v219, 1, v94
	s_nop 0
	v_cndmask_b32_e64 v95, v94, v95, s[0:1]
	v_fma_f32 v94, -v219, v94, v83
	v_cmp_lt_f32_e64 s[0:1], 0, v94
	s_nop 1
	v_cndmask_b32_e64 v94, v95, v219, s[0:1]
	v_mul_f32_e32 v95, 0x37800000, v94
	v_cndmask_b32_e32 v94, v94, v95, vcc
	v_cmp_class_f32_e32 vcc, v83, v179
	s_nop 1
	v_cndmask_b32_e32 v83, v94, v83, vcc
	v_max_f32_e32 v83, 0x2b8cbccc, v83
	v_div_scale_f32 v94, s[0:1], v83, v83, 1.0
	v_rcp_f32_e32 v95, v94
	s_nop 0
	v_fma_f32 v219, -v94, v95, 1.0
	v_fmac_f32_e32 v95, v219, v95
	v_div_scale_f32 v219, vcc, 1.0, v83, 1.0
	v_mul_f32_e32 v220, v219, v95
	v_fma_f32 v221, -v94, v220, v219
	v_fmac_f32_e32 v220, v221, v95
	v_fma_f32 v94, -v94, v220, v219
	v_div_fmas_f32 v94, v94, v95, v220
	v_lshlrev_b32_e32 v95, 10, v212
	v_cndmask_b32_e64 v212, v3, v1, s[6:7]
	s_waitcnt vmcnt(1)
	v_add_f32_e32 v76, v76, v212
	v_mul_f32_e32 v76, 0xbfb8aa3b, v76
	v_exp_f32_e32 v76, v76
	v_div_fixup_f32 v83, v94, v83, 1.0
	v_mul_f32_e32 v88, v88, v83
	v_lshrrev_b32_e32 v94, 8, v194
	v_add_f32_e32 v76, 1.0, v76
	v_div_scale_f32 v212, s[0:1], v76, v76, 1.0
	v_rcp_f32_e32 v219, v212
	v_and_b32_e32 v94, 0x3f0, v94
	v_fma_f32 v220, -v212, v219, 1.0
	v_fmac_f32_e32 v219, v220, v219
	v_div_scale_f32 v220, vcc, 1.0, v76, 1.0
	v_mul_f32_e32 v221, v220, v219
	v_fma_f32 v222, -v212, v221, v220
	v_fmac_f32_e32 v221, v222, v219
	v_fma_f32 v212, -v212, v221, v220
	v_div_fmas_f32 v212, v212, v219, v221
	v_div_fixup_f32 v76, v212, v76, 1.0
	v_cndmask_b32_e64 v212, v7, v5, s[6:7]
	s_waitcnt vmcnt(0)
	v_add_f32_e32 v72, v72, v212
	v_mul_f32_e32 v72, 0xbfb8aa3b, v72
	v_exp_f32_e32 v72, v72
	v_mul_f32_e32 v76, 0xbf1b459e, v76
	v_mul_f32_e32 v76, 0x3fb8aa3b, v76
	v_exp_f32_e32 v76, v76
	v_add_f32_e32 v72, 1.0, v72
	v_div_scale_f32 v212, s[0:1], v72, v72, 1.0
	v_rcp_f32_e32 v219, v212
	v_cvt_f16_f32_e32 v76, v76
	v_fma_f32 v220, -v212, v219, 1.0
	v_fmac_f32_e32 v219, v220, v219
	v_div_scale_f32 v220, vcc, 1.0, v72, 1.0
	v_mul_f32_e32 v221, v220, v219
	v_fma_f32 v222, -v212, v221, v220
	v_fmac_f32_e32 v221, v222, v219
	v_fma_f32 v212, -v212, v221, v220
	v_div_fmas_f32 v212, v212, v219, v221
	v_div_fixup_f32 v72, v212, v72, 1.0
	v_cvt_f16_f32_e64 v212, -v88
	v_fma_mixlo_f16 v88, v92, v88, 0
	v_fma_mixlo_f16 v92, v64, v210, v209
	v_cndmask_b32_e64 v64, v51, v49, s[6:7]
	v_cvt_pk_bf16_f32 v209, v64, s0
	v_mul_f32_e32 v64, v217, v80
	v_cvt_pk_bf16_f32 v210, v64, s0
	v_cndmask_b32_e64 v64, v15, v13, s[6:7]
	v_add_f32_e32 v64, v77, v64
	v_mul_f32_e32 v64, 0xbfb8aa3b, v64
	v_exp_f32_e32 v64, v64
	v_mul_f32_e32 v72, 0xbf1b459e, v72
	v_mul_f32_e32 v72, 0x3fb8aa3b, v72
	v_exp_f32_e32 v72, v72
	v_add_f32_e32 v64, 1.0, v64
	v_div_scale_f32 v77, s[0:1], v64, v64, 1.0
	v_rcp_f32_e32 v214, v77
	v_cvt_f16_f32_e32 v72, v72
	v_fma_f32 v216, -v77, v214, 1.0
	v_fmac_f32_e32 v214, v216, v214
	v_div_scale_f32 v216, vcc, 1.0, v64, 1.0
	v_mul_f32_e32 v217, v216, v214
	v_fma_f32 v218, -v77, v217, v216
	v_fmac_f32_e32 v217, v218, v214
	v_fma_f32 v77, -v77, v217, v216
	v_div_fmas_f32 v77, v77, v214, v217
	v_div_fixup_f32 v64, v77, v64, 1.0
	v_cndmask_b32_e64 v77, v19, v17, s[6:7]
	v_add_f32_e32 v73, v73, v77
	v_mul_f32_e32 v73, 0xbfb8aa3b, v73
	v_exp_f32_e32 v73, v73
	v_mul_f32_e32 v64, 0xbf1b459e, v64
	v_mul_f32_e32 v64, 0x3fb8aa3b, v64
	v_exp_f32_e32 v64, v64
	v_add_f32_e32 v73, 1.0, v73
	v_div_scale_f32 v77, s[0:1], v73, v73, 1.0
	v_rcp_f32_e32 v214, v77
	v_cvt_f16_f32_sdwa v64, v64 dst_sel:WORD_1 dst_unused:UNUSED_PAD src0_sel:DWORD
	v_fma_f32 v216, -v77, v214, 1.0
	v_fmac_f32_e32 v214, v216, v214
	v_div_scale_f32 v216, vcc, 1.0, v73, 1.0
	v_mul_f32_e32 v217, v216, v214
	v_fma_f32 v218, -v77, v217, v216
	v_fmac_f32_e32 v217, v218, v214
	v_fma_f32 v77, -v77, v217, v216
	v_div_fmas_f32 v77, v77, v214, v217
	v_div_fixup_f32 v73, v77, v73, 1.0
	v_mul_f32_e32 v77, v89, v83
	v_cvt_f16_f32_sdwa v89, -v77 dst_sel:WORD_1 dst_unused:UNUSED_PAD src0_sel:DWORD
	v_fma_mixlo_f16 v77, v93, v77, 0
	v_fma_mixlo_f16 v93, v65, v204, v203
	v_cndmask_b32_e64 v65, v55, v53, s[6:7]
	v_cvt_pk_bf16_f32 v203, v65, s0
	v_mul_f32_e32 v65, v213, v80
	v_cvt_pk_bf16_f32 v204, v65, s0
	v_cndmask_b32_e64 v65, v27, v25, s[6:7]
	v_add_f32_e32 v65, v78, v65
	v_mul_f32_e32 v65, 0xbfb8aa3b, v65
; DEVINL u16 f2bf(float a) { return (u16)(pk2(a, 0.f) & 0xffffu); }
; DEVINL float sigm(float x) { return 1.f / (1.f + __expf(-x)); }
; DEVINL void rw_prep_unit(const Params& p, int unit) {
;     ...
; #pragma unroll
;         for (int n = 0; n < 4; ++n) {
;           float wf = __expf(-0.606531f * sigm(w0f[n] + sel4(awf[n], j)));
;           float wb = __expf(-0.606531f * sigm(w0b[n] + sel4(awb[n], j)));
;           float kkn = kkv[n] * inv;
;           hwf[n] = f2h(wf); hwb[n] = f2h(wb); ha[n] = f2h(-kkn); hb[n] = f2h(kkn * av[n]);
;           hk[n] = f2h(pk[n]); hr[n] = f2h(pr[n]); hv[n] = f2h(pv[n]);
;           bg[n] = f2bf(sel4(ag[n], j)); bbn[n] = f2bf(dot * pv[n]);
;         }
;         char* rb = ws + O_REC + (reco + (unsigned)l15 * 64u);
;         *(uint4*)(rb) = make_uint4(hwf[0] | (hwf[1] << 16), hwf[2] | (hwf[3] << 16), hwb[0] | (hwb[1] << 16), hwb[2] | (hwb[3] << 16));
;         *(uint4*)(rb + 16) = make_uint4(ha[0] | (ha[1] << 16), ha[2] | (ha[3] << 16), hb[0] | (hb[1] << 16), hb[2] | (hb[3] << 16));
;         *(uint4*)(rb + 32) = make_uint4(hk[0] | (hk[1] << 16), hk[2] | (hk[3] << 16), hr[0] | (hr[1] << 16), hr[2] | (hr[3] << 16));
;         *(uint2*)(rb + 48) = make_uint2(hv[0] | (hv[1] << 16), hv[2] | (hv[3] << 16));
;         *(uint2*)(ws + O_GRW + tco) = make_uint2(bg[0] | (bg[1] << 16), bg[2] | (bg[3] << 16));
;         *(uint2*)(ws + O_BONUS + tco) = make_uint2(bbn[0] | (bbn[1] << 16), bbn[2] | (bbn[3] << 16));
;       }
;     }
;   }
;   __syncthreads();
	v_exp_f32_e32 v65, v65
	v_mul_f32_e32 v73, 0xbf1b459e, v73
	v_mul_f32_e32 v73, 0x3fb8aa3b, v73
	v_exp_f32_e32 v73, v73
	v_add_f32_e32 v65, 1.0, v65
	v_div_scale_f32 v78, s[0:1], v65, v65, 1.0
	v_rcp_f32_e32 v206, v78
	v_cvt_f16_f32_sdwa v73, v73 dst_sel:WORD_1 dst_unused:UNUSED_PAD src0_sel:DWORD
	v_or_b32_e32 v64, v64, v76
	v_fma_f32 v211, -v78, v206, 1.0
	v_fmac_f32_e32 v206, v211, v206
	v_div_scale_f32 v211, vcc, 1.0, v65, 1.0
	v_mul_f32_e32 v213, v211, v206
	v_fma_f32 v214, -v78, v213, v211
	v_fmac_f32_e32 v213, v214, v206
	v_fma_f32 v78, -v78, v213, v211
	v_div_fmas_f32 v78, v78, v206, v213
	v_div_fixup_f32 v65, v78, v65, 1.0
	v_cndmask_b32_e64 v78, v31, v29, s[6:7]
	v_add_f32_e32 v74, v74, v78
	v_mul_f32_e32 v74, 0xbfb8aa3b, v74
	v_exp_f32_e32 v74, v74
	v_mul_f32_e32 v65, 0xbf1b459e, v65
	v_mul_f32_e32 v65, 0x3fb8aa3b, v65
	v_exp_f32_e32 v65, v65
	v_add_f32_e32 v74, 1.0, v74
	v_div_scale_f32 v78, s[0:1], v74, v74, 1.0
	v_rcp_f32_e32 v206, v78
	v_cvt_f16_f32_e32 v65, v65
	v_fma_f32 v211, -v78, v206, 1.0
	v_fmac_f32_e32 v206, v211, v206
	v_div_scale_f32 v211, vcc, 1.0, v74, 1.0
	v_mul_f32_e32 v213, v211, v206
	v_fma_f32 v214, -v78, v213, v211
	v_fmac_f32_e32 v213, v214, v206
	v_fma_f32 v78, -v78, v213, v211
	v_div_fmas_f32 v78, v78, v206, v213
	v_div_fixup_f32 v74, v78, v74, 1.0
	v_mul_f32_e32 v78, v90, v83
	v_cvt_f16_f32_e64 v90, -v78
	v_fma_mixlo_f16 v78, v81, v78, 0
	v_fma_mixlo_f16 v81, v200, v86, 0
	v_fma_mixlo_f16 v86, v66, v198, v197
	v_cndmask_b32_e64 v66, v59, v57, s[6:7]
	v_cvt_pk_bf16_f32 v197, v66, s0
	v_mul_f32_e32 v66, v207, v80
	v_cvt_pk_bf16_f32 v198, v66, s0
	v_cndmask_b32_e64 v66, v39, v37, s[6:7]
	v_add_f32_e32 v66, v79, v66
	v_mul_f32_e32 v66, 0xbfb8aa3b, v66
	v_exp_f32_e32 v66, v66
	v_mul_f32_e32 v74, 0xbf1b459e, v74
	v_mul_f32_e32 v74, 0x3fb8aa3b, v74
	v_exp_f32_e32 v74, v74
	v_add_f32_e32 v66, 1.0, v66
	v_div_scale_f32 v79, s[0:1], v66, v66, 1.0
	v_rcp_f32_e32 v200, v79
	v_cvt_f16_f32_e32 v74, v74
	v_fma_f32 v205, -v79, v200, 1.0
	v_fmac_f32_e32 v200, v205, v200
	v_div_scale_f32 v205, vcc, 1.0, v66, 1.0
	v_mul_f32_e32 v206, v205, v200
	v_fma_f32 v207, -v79, v206, v205
	v_fmac_f32_e32 v206, v207, v200
	v_fma_f32 v79, -v79, v206, v205
	v_div_fmas_f32 v79, v79, v200, v206
	v_div_fixup_f32 v66, v79, v66, 1.0
	v_cndmask_b32_e64 v79, v43, v41, s[6:7]
	v_add_f32_e32 v75, v75, v79
	v_mul_f32_e32 v75, 0xbfb8aa3b, v75
	v_exp_f32_e32 v75, v75
	v_mul_f32_e32 v66, 0xbf1b459e, v66
	v_mul_f32_e32 v66, 0x3fb8aa3b, v66
	v_exp_f32_e32 v66, v66
	v_add_f32_e32 v75, 1.0, v75
	v_div_scale_f32 v79, s[0:1], v75, v75, 1.0
	v_rcp_f32_e32 v200, v79
	v_cvt_f16_f32_sdwa v66, v66 dst_sel:WORD_1 dst_unused:UNUSED_PAD src0_sel:DWORD
	v_fma_f32 v205, -v79, v200, 1.0
	v_fmac_f32_e32 v200, v205, v200
	v_div_scale_f32 v205, vcc, 1.0, v75, 1.0
	v_mul_f32_e32 v206, v205, v200
	v_fma_f32 v207, -v79, v206, v205
	v_fmac_f32_e32 v206, v207, v200
	v_fma_f32 v79, -v79, v206, v205
	v_div_fmas_f32 v79, v79, v200, v206
	v_div_fixup_f32 v75, v79, v75, 1.0
	v_mul_f32_e32 v75, 0xbf1b459e, v75
	v_mul_f32_e32 v75, 0x3fb8aa3b, v75
	v_exp_f32_e32 v75, v75
	v_mul_f32_e32 v79, v91, v83
	v_cvt_f16_f32_sdwa v83, -v79 dst_sel:WORD_1 dst_unused:UNUSED_PAD src0_sel:DWORD
	v_fma_mixlo_f16 v79, v82, v79, 0
	v_cvt_f16_f32_sdwa v75, v75 dst_sel:WORD_1 dst_unused:UNUSED_PAD src0_sel:DWORD
	v_fma_mixlo_f16 v82, v196, v87, 0
	v_fma_mixlo_f16 v87, v67, v195, v96
	v_cndmask_b32_e64 v67, v63, v61, s[6:7]
	v_cvt_pk_bf16_f32 v91, v67, s0
	v_mul_f32_e32 v67, v201, v80
	v_cvt_pk_bf16_f32 v80, v67, s0
	v_add_lshl_u32 v67, v94, v191, 22
	v_or3_b32 v95, v67, v95, v186
	v_or_b32_e32 v65, v66, v65
	v_or_b32_e32 v67, v75, v74
	v_or_b32_e32 v66, v73, v72
	global_store_dwordx4 v95, v[64:67], s[36:37] nt
	v_lshlrev_b32_e32 v72, 16, v77
	v_lshl_add_u32 v94, v194, 11, v178
	v_lshlrev_b32_e32 v66, 16, v79
	v_or_b32_e32 v65, v83, v90
	v_or_b32_e32 v64, v89, v212
	v_or_b32_sdwa v67, v66, v78 dst_sel:DWORD dst_unused:UNUSED_PAD src0_sel:DWORD src1_sel:WORD_0
	v_or_b32_sdwa v66, v72, v88 dst_sel:DWORD dst_unused:UNUSED_PAD src0_sel:DWORD src1_sel:WORD_0
	global_store_dwordx4 v95, v[64:67], s[36:37] offset:256 nt
	v_lshlrev_b32_e32 v72, 16, v93
	s_nop 0
	v_lshlrev_b32_e32 v64, 16, v82
	v_lshlrev_b32_e32 v66, 16, v85
	v_lshlrev_b32_e32 v67, 16, v87
	v_or_b32_sdwa v65, v64, v81 dst_sel:DWORD dst_unused:UNUSED_PAD src0_sel:DWORD src1_sel:WORD_0
	v_or_b32_sdwa v64, v66, v84 dst_sel:DWORD dst_unused:UNUSED_PAD src0_sel:DWORD src1_sel:WORD_0
	v_or_b32_sdwa v67, v67, v86 dst_sel:DWORD dst_unused:UNUSED_PAD src0_sel:DWORD src1_sel:WORD_0
	v_or_b32_sdwa v66, v72, v92 dst_sel:DWORD dst_unused:UNUSED_PAD src0_sel:DWORD src1_sel:WORD_0
	global_store_dwordx4 v95, v[64:67], s[36:37] offset:512 nt
	s_nop 1
	v_lshlrev_b32_e32 v64, 16, v71
	v_lshlrev_b32_e32 v66, 16, v69
	v_or_b32_sdwa v65, v64, v70 dst_sel:DWORD dst_unused:UNUSED_PAD src0_sel:DWORD src1_sel:WORD_0
	v_or_b32_sdwa v64, v66, v68 dst_sel:DWORD dst_unused:UNUSED_PAD src0_sel:DWORD src1_sel:WORD_0
	global_store_dwordx2 v95, v[64:65], s[36:37] offset:768 nt
	v_lshlrev_b32_e32 v64, 16, v91
	v_lshlrev_b32_e32 v66, 16, v203
	v_or_b32_sdwa v65, v64, v197 dst_sel:DWORD dst_unused:UNUSED_PAD src0_sel:DWORD src1_sel:WORD_0
	v_or_b32_sdwa v64, v66, v209 dst_sel:DWORD dst_unused:UNUSED_PAD src0_sel:DWORD src1_sel:WORD_0
	global_store_dwordx2 v94, v[64:65], s[38:39] nt
	v_lshlrev_b32_e32 v64, 16, v80
	v_lshlrev_b32_e32 v66, 16, v204
	v_or_b32_sdwa v65, v64, v198 dst_sel:DWORD dst_unused:UNUSED_PAD src0_sel:DWORD src1_sel:WORD_0
	v_or_b32_sdwa v64, v66, v210 dst_sel:DWORD dst_unused:UNUSED_PAD src0_sel:DWORD src1_sel:WORD_0
	global_store_dwordx2 v94, v[64:65], s[70:71] nt
	s_cbranch_scc0 .LBB0_383
	s_mov_b32 s6, 16
	s_mov_b64 s[0:1], 0
	s_and_b64 vcc, exec, s[82:83]
	s_cbranch_vccz .LBB0_382
	s_mov_b32 s6, 1
	s_and_b64 vcc, exec, s[80:81]
	s_cbranch_vccz .LBB0_381
	s_add_i32 s51, s51, s94
	s_add_i32 s3, s3, s42
	s_cmpk_lt_i32 s51, 0x100
	s_barrier
	s_cbranch_scc1 .LBB0_336
